# attention epilogue: pairs of row-per-lane dwordx2 stores merged into dwordx4 via v_permlane32_swap, stacked on the census-parallel + flat-release + arrival-invalidate barrier version
# baseline (speedup 1.0000x reference)
; DI float shflx(float v, int mask) { return __uint_as_float((unsigned)__builtin_amdgcn_ds_bpermute((lane_id_opaque() ^ mask) << 2, (int)__float_as_uint(v))); }
; template <bool DIFF> DI void attn_unit(LAS unsigned char* L, const bf16* Qh, int qpitch, const bf16* Kh, const bf16* Vh, int kvpitch, bf16* Oh, int opitch, ...
;     ...
;         if (mp == 0) {
;             float ss = 0.f;
; #pragma unroll
;             for (int d0 = 0; d0 < 4; ++d0)
; #pragma unroll
;                 for (int i = 0; i < 16; ++i) { const float o = y[d0][i] * inv - lam * exch[((qs * 4 + d0) * 16 + i) * 64 + le_]; y[d0][i] = o; ss += o * o; }
;             ss += shflx(ss, 32);
;             const float rr = rsqrtf(ss * (1.f / 128.f) + EPS) * postscale;
; #pragma unroll
;             for (int d0 = 0; d0 < 4; ++d0)
; #pragma unroll
;                 for (int g = 0; g < 4; ++g) { const int dv0 = 32 * d0 + 8 * g + 4 * h_e; const f32x4 sg = *(const f32x4*)(subg + dv0);
.LBB0_220:
	s_andn2_b64 vcc, exec, s[20:21]
	s_waitcnt lgkmcnt(0)
	s_barrier
	s_cbranch_vccnz .LBB0_166
	ds_read2st64_b32 v[78:79], v64 offset1:1
	ds_read2st64_b32 v[80:81], v64 offset0:2 offset1:3
	ds_read2st64_b32 v[82:83], v64 offset0:4 offset1:5
	ds_read2st64_b32 v[84:85], v64 offset0:6 offset1:7
	ds_read2st64_b32 v[90:91], v64 offset0:8 offset1:9
	ds_read2st64_b32 v[92:93], v64 offset0:10 offset1:11
	ds_read2st64_b32 v[96:97], v64 offset0:12 offset1:13
	ds_read2st64_b32 v[98:99], v64 offset0:14 offset1:15
	ds_read2st64_b32 v[100:101], v64 offset0:16 offset1:17
	ds_read2st64_b32 v[102:103], v64 offset0:18 offset1:19
	ds_read2st64_b32 v[104:105], v64 offset0:20 offset1:21
	ds_read2st64_b32 v[106:107], v64 offset0:22 offset1:23
	ds_read2st64_b32 v[108:109], v64 offset0:24 offset1:25
	ds_read2st64_b32 v[110:111], v64 offset0:26 offset1:27
	ds_read2st64_b32 v[112:113], v64 offset0:28 offset1:29
	ds_read2st64_b32 v[114:115], v64 offset0:30 offset1:31
	ds_read2st64_b32 v[116:117], v64 offset0:32 offset1:33
	ds_read2st64_b32 v[118:119], v64 offset0:34 offset1:35
	ds_read2st64_b32 v[120:121], v64 offset0:36 offset1:37
	ds_read2st64_b32 v[122:123], v64 offset0:38 offset1:39
	ds_read2st64_b32 v[124:125], v64 offset0:40 offset1:41
	ds_read2st64_b32 v[126:127], v64 offset0:42 offset1:43
	s_waitcnt vmcnt(3)
	ds_read2st64_b32 v[128:129], v64 offset0:44 offset1:45
	ds_read2st64_b32 v[130:131], v64 offset0:46 offset1:47
	s_waitcnt vmcnt(2)
	ds_read2st64_b32 v[132:133], v64 offset0:56 offset1:57
	ds_read2st64_b32 v[134:135], v64 offset0:58 offset1:59
	ds_read2st64_b32 v[66:67], v64 offset0:60 offset1:61
	ds_read2st64_b32 v[68:69], v64 offset0:62 offset1:63
	s_waitcnt vmcnt(1)
	ds_read2st64_b32 v[136:137], v64 offset0:48 offset1:49
	ds_read2st64_b32 v[138:139], v64 offset0:50 offset1:51
	s_waitcnt vmcnt(0)
	ds_read2st64_b32 v[140:141], v64 offset0:52 offset1:53
	ds_read2st64_b32 v[142:143], v64 offset0:54 offset1:55
	s_waitcnt lgkmcnt(14)
	v_pk_mul_f32 v[78:79], s[12:13], v[78:79]
	v_pk_mul_f32 v[80:81], s[12:13], v[80:81]
	v_pk_fma_f32 v[86:87], v[0:1], v[70:71], v[78:79] op_sel_hi:[1,0,1] neg_lo:[0,0,1] neg_hi:[0,0,1]
	v_pk_mul_f32 v[0:1], s[12:13], v[84:85]
	v_pk_fma_f32 v[2:3], v[2:3], v[70:71], v[80:81] op_sel_hi:[1,0,1] neg_lo:[0,0,1] neg_hi:[0,0,1]
	v_pk_fma_f32 v[78:79], v[6:7], v[70:71], v[0:1] op_sel_hi:[1,0,1] neg_lo:[0,0,1] neg_hi:[0,0,1]
	v_pk_mul_f32 v[0:1], s[12:13], v[82:83]
	s_waitcnt lgkmcnt(5)
	v_pk_mul_f32 v[64:65], s[12:13], v[66:67]
	v_pk_fma_f32 v[88:89], v[4:5], v[70:71], v[0:1] op_sel_hi:[1,0,1] neg_lo:[0,0,1] neg_hi:[0,0,1]
	v_pk_mul_f32 v[0:1], s[12:13], v[92:93]
	v_pk_fma_f32 v[64:65], v[60:61], v[70:71], v[64:65] op_sel_hi:[1,0,1] neg_lo:[0,0,1] neg_hi:[0,0,1]
	v_pk_fma_f32 v[80:81], v[10:11], v[70:71], v[0:1] op_sel_hi:[1,0,1] neg_lo:[0,0,1] neg_hi:[0,0,1]
	v_pk_mul_f32 v[0:1], s[12:13], v[90:91]
	s_waitcnt lgkmcnt(4)
	v_pk_mul_f32 v[60:61], s[12:13], v[68:69]
	v_pk_fma_f32 v[94:95], v[8:9], v[70:71], v[0:1] op_sel_hi:[1,0,1] neg_lo:[0,0,1] neg_hi:[0,0,1]
	v_pk_mul_f32 v[0:1], s[12:13], v[98:99]
	s_mov_b32 s1, -1
	v_pk_fma_f32 v[82:83], v[14:15], v[70:71], v[0:1] op_sel_hi:[1,0,1] neg_lo:[0,0,1] neg_hi:[0,0,1]
	v_pk_mul_f32 v[0:1], s[12:13], v[96:97]
	v_pk_fma_f32 v[66:67], v[62:63], v[70:71], v[60:61] op_sel_hi:[1,0,1] neg_lo:[0,0,1] neg_hi:[0,0,1]
	v_pk_fma_f32 v[96:97], v[12:13], v[70:71], v[0:1] op_sel_hi:[1,0,1] neg_lo:[0,0,1] neg_hi:[0,0,1]
	v_pk_mul_f32 v[0:1], s[12:13], v[102:103]
	s_waitcnt lgkmcnt(1)
	v_pk_mul_f32 v[4:5], s[12:13], v[140:141]
	v_pk_fma_f32 v[84:85], v[34:35], v[70:71], v[0:1] op_sel_hi:[1,0,1] neg_lo:[0,0,1] neg_hi:[0,0,1]
	v_pk_mul_f32 v[0:1], s[12:13], v[100:101]
	v_mbcnt_lo_u32_b32 v60, s1, 0
	v_pk_fma_f32 v[90:91], v[32:33], v[70:71], v[0:1] op_sel_hi:[1,0,1] neg_lo:[0,0,1] neg_hi:[0,0,1]
	v_pk_mul_f32 v[0:1], s[12:13], v[106:107]
	v_mbcnt_hi_u32_b32 v60, s1, v60
	v_pk_fma_f32 v[14:15], v[38:39], v[70:71], v[0:1] op_sel_hi:[1,0,1] neg_lo:[0,0,1] neg_hi:[0,0,1]
	v_pk_mul_f32 v[0:1], s[12:13], v[104:105]
	v_lshlrev_b32_e32 v60, 2, v60
	v_pk_fma_f32 v[92:93], v[36:37], v[70:71], v[0:1] op_sel_hi:[1,0,1] neg_lo:[0,0,1] neg_hi:[0,0,1]
	v_pk_mul_f32 v[0:1], s[12:13], v[110:111]
	v_xor_b32_e32 v208, 0x80, v60
	v_pk_fma_f32 v[32:33], v[42:43], v[70:71], v[0:1] op_sel_hi:[1,0,1] neg_lo:[0,0,1] neg_hi:[0,0,1]
	v_pk_mul_f32 v[0:1], s[12:13], v[108:109]
	v_ashrrev_i32_e32 v60, 3, v71
	v_pk_fma_f32 v[40:41], v[40:41], v[70:71], v[0:1] op_sel_hi:[1,0,1] neg_lo:[0,0,1] neg_hi:[0,0,1]
	v_pk_mul_f32 v[0:1], s[12:13], v[114:115]
	v_and_b32_e32 v74, -4, v60
	v_pk_fma_f32 v[34:35], v[46:47], v[70:71], v[0:1] op_sel_hi:[1,0,1] neg_lo:[0,0,1] neg_hi:[0,0,1]
	v_pk_mul_f32 v[0:1], s[12:13], v[112:113]
	v_ashrrev_i32_e32 v75, 31, v74
	v_pk_fma_f32 v[42:43], v[44:45], v[70:71], v[0:1] op_sel_hi:[1,0,1] neg_lo:[0,0,1] neg_hi:[0,0,1]
	v_pk_mul_f32 v[0:1], s[12:13], v[118:119]
	v_lshl_add_u64 v[68:69], v[74:75], 2, s[14:15]
	v_pk_fma_f32 v[18:19], v[18:19], v[70:71], v[0:1] op_sel_hi:[1,0,1] neg_lo:[0,0,1] neg_hi:[0,0,1]
	v_pk_mul_f32 v[0:1], s[12:13], v[116:117]
	v_pk_mul_f32 v[198:199], v[86:87], v[86:87]
	v_pk_fma_f32 v[36:37], v[16:17], v[70:71], v[0:1] op_sel_hi:[1,0,1] neg_lo:[0,0,1] neg_hi:[0,0,1]
	v_pk_mul_f32 v[0:1], s[12:13], v[122:123]
	global_load_dwordx4 v[232:235], v[68:69], off
	global_load_dwordx4 v[236:239], v[68:69], off offset:32
	global_load_dwordx4 v[240:243], v[68:69], off offset:64
	global_load_dwordx4 v[244:247], v[68:69], off offset:96
	global_load_dwordx4 v[248:251], v[68:69], off offset:128
	v_pk_fma_f32 v[6:7], v[22:23], v[70:71], v[0:1] op_sel_hi:[1,0,1] neg_lo:[0,0,1] neg_hi:[0,0,1]
; DI unsigned pk2(float lo, float hi) { f32x2_t v = {lo, hi}; bf16x2_t b = __builtin_convertvector(v, bf16x2_t); return __builtin_bit_cast(unsigned, b); }
; DI float shflx(float v, int mask) { return __uint_as_float((unsigned)__builtin_amdgcn_ds_bpermute((lane_id_opaque() ^ mask) << 2, (int)__float_as_uint(v))); }
; template <bool DIFF> DI void attn_unit(LAS unsigned char* L, const bf16* Qh, int qpitch, const bf16* Kh, const bf16* Vh, int kvpitch, bf16* Oh, int opitch, ...
;     ...
;             for (int d0 = 0; d0 < 4; ++d0)
; #pragma unroll
;                 for (int i = 0; i < 16; ++i) { const float o = y[d0][i] * inv - lam * exch[((qs * 4 + d0) * 16 + i) * 64 + le_]; y[d0][i] = o; ss += o * o; }
;             ss += shflx(ss, 32);
;             const float rr = rsqrtf(ss * (1.f / 128.f) + EPS) * postscale;
; #pragma unroll
;             for (int d0 = 0; d0 < 4; ++d0)
; #pragma unroll
;                 for (int g = 0; g < 4; ++g) { const int dv0 = 32 * d0 + 8 * g + 4 * h_e; const f32x4 sg = *(const f32x4*)(subg + dv0);
;                     u32x2 w; w.x = pk2(y[d0][4 * g] * rr * sg.x, y[d0][4 * g + 1] * rr * sg.y); w.y = pk2(y[d0][4 * g + 2] * rr * sg.z, y[d0][4 * g + 3] * rr * sg.w);
	v_pk_mul_f32 v[0:1], s[12:13], v[120:121]
	v_pk_mul_f32 v[22:23], s[12:13], v[132:133]
	v_pk_fma_f32 v[38:39], v[20:21], v[70:71], v[0:1] op_sel_hi:[1,0,1] neg_lo:[0,0,1] neg_hi:[0,0,1]
	v_pk_mul_f32 v[0:1], s[12:13], v[126:127]
	v_pk_fma_f32 v[20:21], v[52:53], v[70:71], v[4:5] op_sel_hi:[1,0,1] neg_lo:[0,0,1] neg_hi:[0,0,1]
	v_pk_fma_f32 v[8:9], v[26:27], v[70:71], v[0:1] op_sel_hi:[1,0,1] neg_lo:[0,0,1] neg_hi:[0,0,1]
	v_pk_mul_f32 v[0:1], s[12:13], v[124:125]
	v_pk_mul_f32 v[4:5], s[12:13], v[134:135]
	v_pk_fma_f32 v[24:25], v[24:25], v[70:71], v[0:1] op_sel_hi:[1,0,1] neg_lo:[0,0,1] neg_hi:[0,0,1]
	v_pk_mul_f32 v[0:1], s[12:13], v[130:131]
	v_pk_mul_f32 v[196:197], v[2:3], v[2:3]
	v_pk_fma_f32 v[10:11], v[30:31], v[70:71], v[0:1] op_sel_hi:[1,0,1] neg_lo:[0,0,1] neg_hi:[0,0,1]
	v_pk_mul_f32 v[0:1], s[12:13], v[128:129]
	v_pk_fma_f32 v[4:5], v[58:59], v[70:71], v[4:5] op_sel_hi:[1,0,1] neg_lo:[0,0,1] neg_hi:[0,0,1]
	v_pk_fma_f32 v[26:27], v[28:29], v[70:71], v[0:1] op_sel_hi:[1,0,1] neg_lo:[0,0,1] neg_hi:[0,0,1]
	v_pk_mul_f32 v[0:1], s[12:13], v[138:139]
	v_pk_fma_f32 v[22:23], v[56:57], v[70:71], v[22:23] op_sel_hi:[1,0,1] neg_lo:[0,0,1] neg_hi:[0,0,1]
	v_pk_fma_f32 v[12:13], v[50:51], v[70:71], v[0:1] op_sel_hi:[1,0,1] neg_lo:[0,0,1] neg_hi:[0,0,1]
	v_pk_mul_f32 v[0:1], s[12:13], v[136:137]
	v_pk_mul_f32 v[222:223], v[88:89], v[88:89]
	v_pk_fma_f32 v[16:17], v[48:49], v[70:71], v[0:1] op_sel_hi:[1,0,1] neg_lo:[0,0,1] neg_hi:[0,0,1]
	s_waitcnt lgkmcnt(0)
	v_pk_mul_f32 v[0:1], s[12:13], v[142:143]
	v_pk_mul_f32 v[220:221], v[78:79], v[78:79]
	v_pk_fma_f32 v[0:1], v[54:55], v[70:71], v[0:1] op_sel_hi:[1,0,1] neg_lo:[0,0,1] neg_hi:[0,0,1]
	v_add_f32_e32 v70, v198, v199
	v_add_f32_e32 v70, v70, v196
	v_add_f32_e32 v70, v70, v197
	v_add_f32_e32 v70, v70, v222
	v_add_f32_e32 v70, v70, v223
	v_add_f32_e32 v70, v70, v220
	v_pk_mul_f32 v[226:227], v[94:95], v[94:95]
	v_add_f32_e32 v70, v70, v221
	v_add_f32_e32 v70, v70, v226
	v_pk_mul_f32 v[224:225], v[80:81], v[80:81]
	v_add_f32_e32 v70, v70, v227
	v_add_f32_e32 v70, v70, v224
	v_pk_mul_f32 v[228:229], v[96:97], v[96:97]
	v_add_f32_e32 v70, v70, v225
	v_add_f32_e32 v70, v70, v228
	v_pk_mul_f32 v[98:99], v[82:83], v[82:83]
	v_add_f32_e32 v70, v70, v229
	v_add_f32_e32 v70, v70, v98
	v_pk_mul_f32 v[100:101], v[90:91], v[90:91]
	v_add_f32_e32 v70, v70, v99
	v_add_f32_e32 v70, v70, v100
	v_pk_mul_f32 v[102:103], v[84:85], v[84:85]
	v_add_f32_e32 v70, v70, v101
	v_add_f32_e32 v70, v70, v102
	v_pk_mul_f32 v[104:105], v[92:93], v[92:93]
	v_add_f32_e32 v70, v70, v103
	v_add_f32_e32 v70, v70, v104
	v_pk_mul_f32 v[106:107], v[14:15], v[14:15]
	v_add_f32_e32 v70, v70, v105
	v_add_f32_e32 v70, v70, v106
	v_pk_mul_f32 v[108:109], v[40:41], v[40:41]
	v_add_f32_e32 v70, v70, v107
	v_add_f32_e32 v70, v70, v108
	v_pk_mul_f32 v[110:111], v[32:33], v[32:33]
	v_add_f32_e32 v70, v70, v109
	v_add_f32_e32 v70, v70, v110
	v_pk_mul_f32 v[44:45], v[42:43], v[42:43]
	v_add_f32_e32 v70, v70, v111
	v_add_f32_e32 v44, v70, v44
	v_pk_mul_f32 v[46:47], v[34:35], v[34:35]
	v_add_f32_e32 v44, v44, v45
	v_add_f32_e32 v44, v44, v46
	v_pk_mul_f32 v[114:115], v[36:37], v[36:37]
	v_add_f32_e32 v44, v44, v47
	v_add_f32_e32 v44, v44, v114
	v_pk_mul_f32 v[112:113], v[18:19], v[18:19]
	v_add_f32_e32 v44, v44, v115
	v_add_f32_e32 v44, v44, v112
	v_pk_mul_f32 v[118:119], v[38:39], v[38:39]
	v_add_f32_e32 v44, v44, v113
	v_add_f32_e32 v44, v44, v118
	v_pk_mul_f32 v[116:117], v[6:7], v[6:7]
	v_add_f32_e32 v44, v44, v119
	v_add_f32_e32 v44, v44, v116
	v_pk_mul_f32 v[122:123], v[24:25], v[24:25]
	v_add_f32_e32 v44, v44, v117
	v_add_f32_e32 v44, v44, v122
	v_pk_mul_f32 v[120:121], v[8:9], v[8:9]
	v_add_f32_e32 v44, v44, v123
	v_add_f32_e32 v44, v44, v120
	v_pk_mul_f32 v[28:29], v[26:27], v[26:27]
	v_add_f32_e32 v44, v44, v121
	v_add_f32_e32 v28, v44, v28
	v_pk_mul_f32 v[30:31], v[10:11], v[10:11]
	v_add_f32_e32 v28, v28, v29
	v_add_f32_e32 v28, v28, v30
	v_pk_mul_f32 v[48:49], v[16:17], v[16:17]
	v_add_f32_e32 v28, v28, v31
	v_add_f32_e32 v28, v28, v48
	v_pk_mul_f32 v[50:51], v[12:13], v[12:13]
	v_add_f32_e32 v28, v28, v49
	v_add_f32_e32 v28, v28, v50
	v_pk_mul_f32 v[52:53], v[20:21], v[20:21]
	v_add_f32_e32 v28, v28, v51
	v_add_f32_e32 v28, v28, v52
	v_pk_mul_f32 v[54:55], v[0:1], v[0:1]
	v_add_f32_e32 v28, v28, v53
	v_add_f32_e32 v28, v28, v54
	v_pk_mul_f32 v[56:57], v[22:23], v[22:23]
	v_add_f32_e32 v28, v28, v55
	v_add_f32_e32 v28, v28, v56
	v_pk_mul_f32 v[58:59], v[4:5], v[4:5]
	v_add_f32_e32 v28, v28, v57
	v_add_f32_e32 v28, v28, v58
	v_pk_mul_f32 v[72:73], v[64:65], v[64:65]
	v_add_f32_e32 v28, v28, v59
	v_add_f32_e32 v28, v28, v72
	v_pk_mul_f32 v[76:77], v[66:67], v[66:67]
	v_add_f32_e32 v28, v28, v73
	v_add_f32_e32 v28, v28, v76
	v_add_f32_e32 v44, v28, v77
	ds_bpermute_b32 v45, v208, v44
	s_lshl_b32 s36, s80, 1
	v_and_or_b32 v30, v71, 31, s74
	v_mov_b32_e32 v31, s75
	v_lshl_add_u64 v[28:29], v[144:145], 0, s[36:37]
	s_waitcnt lgkmcnt(0)
	v_add_f32_e32 v44, v44, v45
	v_fmamk_f32 v44, v44, 0x3c000000, v203
	v_mul_f32_e32 v45, 0x4b800000, v44
	v_cmp_gt_f32_e32 vcc, s2, v44
	v_lshlrev_b64 v[30:31], 12, v[30:31]
	v_lshl_add_u64 v[28:29], v[28:29], 0, v[30:31]
	v_cndmask_b32_e32 v44, v44, v45, vcc
	v_rsq_f32_e32 v46, v44
	v_lshl_add_u64 v[44:45], v[74:75], 1, v[28:29]
	v_mbcnt_lo_u32_b32 v108, -1, 0
	v_mbcnt_hi_u32_b32 v108, -1, v108
	v_mov_b32_e32 v109, 0
	v_and_b32_e32 v108, 32, v108
	v_lshrrev_b32_e32 v108, 2, v108
	v_lshl_add_u64 v[44:45], v[44:45], 0, v[108:109]
	v_mul_f32_e32 v28, 0x45800000, v46
	v_cndmask_b32_e32 v28, v46, v28, vcc
	v_mul_f32_e32 v46, v209, v28
	v_pk_mul_f32 v[28:29], v[86:87], v[46:47] op_sel_hi:[1,0]
	v_pk_mul_f32 v[2:3], v[2:3], v[46:47] op_sel_hi:[1,0]
	s_waitcnt vmcnt(4)
; DI unsigned pk2(float lo, float hi) { f32x2_t v = {lo, hi}; bf16x2_t b = __builtin_convertvector(v, bf16x2_t); return __builtin_bit_cast(unsigned, b); }
; template <bool DIFF> DI void attn_unit(LAS unsigned char* L, const bf16* Qh, int qpitch, const bf16* Kh, const bf16* Vh, int kvpitch, bf16* Oh, int opitch, ...
;     ...
; #pragma unroll
;             for (int d0 = 0; d0 < 4; ++d0)
; #pragma unroll
;                 for (int g = 0; g < 4; ++g) { const int dv0 = 32 * d0 + 8 * g + 4 * h_e; const f32x4 sg = *(const f32x4*)(subg + dv0);
;                     u32x2 w; w.x = pk2(y[d0][4 * g] * rr * sg.x, y[d0][4 * g + 1] * rr * sg.y); w.y = pk2(y[d0][4 * g + 2] * rr * sg.z, y[d0][4 * g + 3] * rr * sg.w);
;                     *(u32x2*)(orow + dv0) = w; }
	v_pk_mul_f32 v[28:29], v[232:233], v[28:29]
	v_pk_mul_f32 v[2:3], v[234:235], v[2:3]
	v_cvt_pk_bf16_f32 v100, v28, v29
	v_cvt_pk_bf16_f32 v101, v2, v3
	global_load_dwordx4 v[232:235], v[68:69], off offset:160
	v_pk_mul_f32 v[2:3], v[88:89], v[46:47] op_sel_hi:[1,0]
	v_pk_mul_f32 v[48:49], v[80:81], v[46:47] op_sel_hi:[1,0]
	v_pk_mul_f32 v[14:15], v[14:15], v[46:47] op_sel_hi:[1,0]
	v_pk_mul_f32 v[6:7], v[6:7], v[46:47] op_sel_hi:[1,0]
	v_pk_mul_f32 v[10:11], v[10:11], v[46:47] op_sel_hi:[1,0]
	v_pk_mul_f32 v[0:1], v[0:1], v[46:47] op_sel_hi:[1,0]
	v_pk_mul_f32 v[4:5], v[4:5], v[46:47] op_sel_hi:[1,0]
	s_waitcnt vmcnt(4)
	v_pk_mul_f32 v[2:3], v[236:237], v[2:3]
	v_pk_mul_f32 v[28:29], v[78:79], v[46:47] op_sel_hi:[1,0]
	v_cvt_pk_bf16_f32 v102, v2, v3
	v_pk_mul_f32 v[28:29], v[238:239], v[28:29]
	s_nop 0
	v_cvt_pk_bf16_f32 v103, v28, v29
	s_nop 1
	v_permlane32_swap_b32_e32 v100, v102
	v_permlane32_swap_b32_e32 v101, v103
	global_store_dwordx4 v[44:45], v[100:103], off
	global_load_dwordx4 v[236:239], v[68:69], off offset:192
	v_pk_mul_f32 v[2:3], v[94:95], v[46:47] op_sel_hi:[1,0]
	s_waitcnt vmcnt(5)
	v_pk_mul_f32 v[2:3], v[240:241], v[2:3]
	v_pk_mul_f32 v[28:29], v[242:243], v[48:49]
	v_cvt_pk_bf16_f32 v104, v2, v3
	v_cvt_pk_bf16_f32 v105, v28, v29
	global_load_dwordx4 v[240:243], v[68:69], off offset:224
	v_pk_mul_f32 v[2:3], v[96:97], v[46:47] op_sel_hi:[1,0]
	v_pk_mul_f32 v[48:49], v[82:83], v[46:47] op_sel_hi:[1,0]
	s_waitcnt vmcnt(5)
	v_pk_mul_f32 v[2:3], v[244:245], v[2:3]
	v_pk_mul_f32 v[28:29], v[246:247], v[48:49]
	v_cvt_pk_bf16_f32 v106, v2, v3
	v_cvt_pk_bf16_f32 v107, v28, v29
	s_nop 1
	v_permlane32_swap_b32_e32 v104, v106
	v_permlane32_swap_b32_e32 v105, v107
	global_store_dwordx4 v[44:45], v[104:107], off offset:32
	global_load_dwordx4 v[244:247], v[68:69], off offset:256
	v_pk_mul_f32 v[2:3], v[90:91], v[46:47] op_sel_hi:[1,0]
	v_pk_mul_f32 v[48:49], v[84:85], v[46:47] op_sel_hi:[1,0]
	s_waitcnt vmcnt(6)
	v_pk_mul_f32 v[2:3], v[248:249], v[2:3]
	v_pk_mul_f32 v[28:29], v[250:251], v[48:49]
	v_cvt_pk_bf16_f32 v100, v2, v3
	v_cvt_pk_bf16_f32 v101, v28, v29
	global_load_dwordx4 v[248:251], v[68:69], off offset:288
	v_pk_mul_f32 v[2:3], v[92:93], v[46:47] op_sel_hi:[1,0]
	s_waitcnt vmcnt(6)
	v_pk_mul_f32 v[14:15], v[14:15], v[234:235]
	v_pk_mul_f32 v[2:3], v[2:3], v[232:233]
	s_nop 0
	v_cvt_pk_bf16_f32 v102, v2, v3
	v_cvt_pk_bf16_f32 v103, v14, v15
	s_nop 1
	v_permlane32_swap_b32_e32 v100, v102
	v_permlane32_swap_b32_e32 v101, v103
	global_store_dwordx4 v[44:45], v[100:103], off offset:64
	global_load_dwordx4 v[232:235], v[68:69], off offset:320
	v_pk_mul_f32 v[2:3], v[40:41], v[46:47] op_sel_hi:[1,0]
	v_pk_mul_f32 v[14:15], v[32:33], v[46:47] op_sel_hi:[1,0]
	s_waitcnt vmcnt(6)
	v_pk_mul_f32 v[2:3], v[2:3], v[236:237]
	v_pk_mul_f32 v[14:15], v[14:15], v[238:239]
	v_cvt_pk_bf16_f32 v104, v2, v3
	v_cvt_pk_bf16_f32 v105, v14, v15
	global_load_dwordx4 v[236:239], v[68:69], off offset:352
	v_pk_mul_f32 v[2:3], v[42:43], v[46:47] op_sel_hi:[1,0]
	v_pk_mul_f32 v[14:15], v[34:35], v[46:47] op_sel_hi:[1,0]
	s_waitcnt vmcnt(6)
	v_pk_mul_f32 v[2:3], v[2:3], v[240:241]
	v_pk_mul_f32 v[14:15], v[14:15], v[242:243]
	v_cvt_pk_bf16_f32 v106, v2, v3
	v_cvt_pk_bf16_f32 v107, v14, v15
	s_nop 1
	v_permlane32_swap_b32_e32 v104, v106
	v_permlane32_swap_b32_e32 v105, v107
	global_store_dwordx4 v[44:45], v[104:107], off offset:96
	global_load_dwordx4 v[240:243], v[68:69], off offset:384
	v_pk_mul_f32 v[2:3], v[36:37], v[46:47] op_sel_hi:[1,0]
	v_pk_mul_f32 v[14:15], v[18:19], v[46:47] op_sel_hi:[1,0]
	s_waitcnt vmcnt(6)
	v_pk_mul_f32 v[2:3], v[2:3], v[244:245]
	v_pk_mul_f32 v[14:15], v[14:15], v[246:247]
	v_cvt_pk_bf16_f32 v100, v2, v3
	v_cvt_pk_bf16_f32 v101, v14, v15
	global_load_dwordx4 v[244:247], v[68:69], off offset:416
	v_pk_mul_f32 v[2:3], v[38:39], v[46:47] op_sel_hi:[1,0]
	s_waitcnt vmcnt(6)
	v_pk_mul_f32 v[6:7], v[6:7], v[250:251]
	v_pk_mul_f32 v[2:3], v[2:3], v[248:249]
	s_nop 0
	v_cvt_pk_bf16_f32 v102, v2, v3
	v_cvt_pk_bf16_f32 v103, v6, v7
	s_nop 1
	v_permlane32_swap_b32_e32 v100, v102
	v_permlane32_swap_b32_e32 v101, v103
	global_store_dwordx4 v[44:45], v[100:103], off offset:128
	global_load_dwordx4 v[248:251], v[68:69], off offset:448
	v_pk_mul_f32 v[2:3], v[24:25], v[46:47] op_sel_hi:[1,0]
	v_pk_mul_f32 v[6:7], v[8:9], v[46:47] op_sel_hi:[1,0]
	s_waitcnt vmcnt(6)
	v_pk_mul_f32 v[2:3], v[2:3], v[232:233]
	v_pk_mul_f32 v[6:7], v[6:7], v[234:235]
	v_cvt_pk_bf16_f32 v104, v2, v3
	v_cvt_pk_bf16_f32 v105, v6, v7
	global_load_dwordx4 v[232:235], v[68:69], off offset:480
	v_pk_mul_f32 v[2:3], v[26:27], v[46:47] op_sel_hi:[1,0]
	s_waitcnt vmcnt(6)
	v_pk_mul_f32 v[2:3], v[2:3], v[236:237]
	v_pk_mul_f32 v[6:7], v[10:11], v[238:239]
	v_cvt_pk_bf16_f32 v106, v2, v3
	v_cvt_pk_bf16_f32 v107, v6, v7
	s_nop 1
	v_permlane32_swap_b32_e32 v104, v106
	v_permlane32_swap_b32_e32 v105, v107
	global_store_dwordx4 v[44:45], v[104:107], off offset:160
	v_pk_mul_f32 v[2:3], v[16:17], v[46:47] op_sel_hi:[1,0]
	v_pk_mul_f32 v[10:11], v[12:13], v[46:47] op_sel_hi:[1,0]
	s_waitcnt vmcnt(5)
	v_pk_mul_f32 v[2:3], v[2:3], v[240:241]
	v_pk_mul_f32 v[6:7], v[10:11], v[242:243]
	v_cvt_pk_bf16_f32 v100, v2, v3
	v_cvt_pk_bf16_f32 v101, v6, v7
	v_pk_mul_f32 v[2:3], v[20:21], v[46:47] op_sel_hi:[1,0]
	s_waitcnt vmcnt(4)
	v_pk_mul_f32 v[0:1], v[0:1], v[246:247]
	v_pk_mul_f32 v[2:3], v[2:3], v[244:245]
	v_pk_mul_f32 v[6:7], v[22:23], v[46:47] op_sel_hi:[1,0]
	v_cvt_pk_bf16_f32 v102, v2, v3
	v_cvt_pk_bf16_f32 v103, v0, v1
	s_nop 1
	v_permlane32_swap_b32_e32 v100, v102
	v_permlane32_swap_b32_e32 v101, v103
	global_store_dwordx4 v[44:45], v[100:103], off offset:192
	s_waitcnt vmcnt(3)
	v_pk_mul_f32 v[0:1], v[6:7], v[248:249]
	v_pk_mul_f32 v[2:3], v[4:5], v[250:251]
	v_cvt_pk_bf16_f32 v104, v0, v1
	v_cvt_pk_bf16_f32 v105, v2, v3
	v_pk_mul_f32 v[4:5], v[64:65], v[46:47] op_sel_hi:[1,0]
	v_pk_mul_f32 v[6:7], v[66:67], v[46:47] op_sel_hi:[1,0]
	s_waitcnt vmcnt(2)
	v_pk_mul_f32 v[0:1], v[4:5], v[232:233]
	v_pk_mul_f32 v[2:3], v[6:7], v[234:235]
	v_cvt_pk_bf16_f32 v106, v0, v1
	v_cvt_pk_bf16_f32 v107, v2, v3
	s_nop 1
	v_permlane32_swap_b32_e32 v104, v106
	v_permlane32_swap_b32_e32 v105, v107
	global_store_dwordx4 v[44:45], v[104:107], off offset:224
	s_branch .LBB0_166
